# GEMM3 sample-unit epilogue: per-step state loads waited before the masked state store is issued (wait no longer covers its own store), on top of the pre-loop hoist
# speedup vs baseline: 1.0034x; 1.0034x over previous
; __device__ __forceinline__ float dpp_shr1(float old, float src) { return __builtin_bit_cast(float, __builtin_amdgcn_update_dpp(__builtin_bit_cast(int, old), __builtin_bit_cast(int, src), 0x111, 0xf, 0xf, false)); }
; __device__ __forceinline__ float dpp_shr2(float old, float src) { return __builtin_bit_cast(float, __builtin_amdgcn_update_dpp(__builtin_bit_cast(int, old), __builtin_bit_cast(int, src), 0x112, 0xf, 0xf, false)); }
;     __device__ __forceinline__ void operator()(const f32x4 (&acc)[2][2][4][2], const Unit& u, int wr, int wc, int fr, int fq) const {
;     ...
;                         const int t = fr & 7, bs = (r - MP) >> 3; f32x4 s0 = (f32x4){0.f, 0.f, 0.f, 0.f}, s1 = s0;
;                         if (t < 2) { s0 = *(const f32x4*)(st_ffn + ((size_t)bs * 2 + 0) * DFF + j0 + 4 * n); s1 = *(const f32x4*)(st_ffn + ((size_t)bs * 2 + 1) * DFF + j0 + 4 * n); }
; #pragma unroll
;                         for (int e = 0; e < 4; ++e) { const float a1 = dpp_shr1(0.f, g[e]), a2 = dpp_shr2(0.f, g[e]); p1[e] = (t >= 1) ? a1 : s1[e]; p2[e] = (t >= 2) ? a2 : (t == 1 ? s1[e] : s0[e]); }
;                         if (t >= 6) *(f32x4*)(out + O_SFFN + ((size_t)bs * 2 + (t - 6)) * DFF + j0 + 4 * n) = g;
.LBB0_763:
	s_or_b64 exec, exec, s[22:23]
	v_mov_b32_e32 v119, v179
	v_mov_b32_e32 v167, v179
	v_mov_b32_e32 v168, v179
	v_mov_b32_e32 v169, v179
	v_mov_b32_e32 v188, v179
	v_mov_b32_e32 v190, v179
	v_mov_b32_e32 v191, v179
	v_mov_b32_e32 v192, v179
	v_mov_b32_dpp v119, v150 row_shr:1 row_mask:0xf bank_mask:0xf
	v_mov_b32_dpp v167, v150 row_shr:2 row_mask:0xf bank_mask:0xf
	v_mov_b32_dpp v168, v151 row_shr:1 row_mask:0xf bank_mask:0xf
	v_mov_b32_dpp v169, v151 row_shr:2 row_mask:0xf bank_mask:0xf
	v_mov_b32_dpp v188, v152 row_shr:1 row_mask:0xf bank_mask:0xf
	v_mov_b32_dpp v190, v152 row_shr:2 row_mask:0xf bank_mask:0xf
	v_mov_b32_dpp v191, v153 row_shr:1 row_mask:0xf bank_mask:0xf
	v_mov_b32_dpp v192, v153 row_shr:2 row_mask:0xf bank_mask:0xf
	s_waitcnt vmcnt(0)
	s_and_saveexec_b64 s[22:23], s[12:13]
	s_cbranch_execz .LBB0_765
	v_ashrrev_i32_e32 v163, 31, v162
	v_lshl_add_u64 v[162:163], v[162:163], 1, v[178:179]
	v_mov_b64_e32 v[222:223], s[62:63]
	v_mad_u64_u32 v[222:223], s[82:83], v162, s26, v[222:223]
	v_mad_i32_i24 v223, v163, s26, v223
	v_lshl_add_u64 v[162:163], v[184:185], 2, v[222:223]
	global_store_dwordx4 v[162:163], v[150:153], off
.LBB0_765:
	s_or_b64 exec, exec, s[22:23]
	v_cndmask_b32_e64 v162, v119, v158, s[10:11]
	v_cndmask_b32_e64 v119, v154, v158, s[8:9]
	v_cndmask_b32_e64 v154, v119, v167, s[6:7]
	v_cndmask_b32_e64 v119, v155, v159, s[8:9]
	v_cndmask_b32_e64 v155, v119, v169, s[6:7]
	v_cndmask_b32_e64 v119, v156, v160, s[8:9]
	v_cndmask_b32_e64 v156, v119, v190, s[6:7]
	v_cndmask_b32_e64 v119, v157, v161, s[8:9]
	v_cndmask_b32_e64 v158, v168, v159, s[10:11]
	v_cndmask_b32_e64 v159, v188, v160, s[10:11]
	v_cndmask_b32_e64 v160, v191, v161, s[10:11]
	v_cndmask_b32_e64 v157, v119, v192, s[6:7]
	s_mov_b64 s[22:23], 0

; __device__ __forceinline__ float dpp_shr1(float old, float src) { return __builtin_bit_cast(float, __builtin_amdgcn_update_dpp(__builtin_bit_cast(int, old), __builtin_bit_cast(int, src), 0x111, 0xf, 0xf, false)); }
; __device__ __forceinline__ float dpp_shr2(float old, float src) { return __builtin_bit_cast(float, __builtin_amdgcn_update_dpp(__builtin_bit_cast(int, old), __builtin_bit_cast(int, src), 0x112, 0xf, 0xf, false)); }
;     __device__ __forceinline__ void operator()(const f32x4 (&acc)[2][2][4][2], const Unit& u, int wr, int wc, int fr, int fq) const {
;     ...
;                         const int t = fr & 7, bs = (r - MP) >> 3; f32x4 s0 = (f32x4){0.f, 0.f, 0.f, 0.f}, s1 = s0;
;                         if (t < 2) { s0 = *(const f32x4*)(st_ffn + ((size_t)bs * 2 + 0) * DFF + j0 + 4 * n); s1 = *(const f32x4*)(st_ffn + ((size_t)bs * 2 + 1) * DFF + j0 + 4 * n); }
; #pragma unroll
;                         for (int e = 0; e < 4; ++e) { const float a1 = dpp_shr1(0.f, g[e]), a2 = dpp_shr2(0.f, g[e]); p1[e] = (t >= 1) ? a1 : s1[e]; p2[e] = (t >= 2) ? a2 : (t == 1 ? s1[e] : s0[e]); }
;                         if (t >= 6) *(f32x4*)(out + O_SFFN + ((size_t)bs * 2 + (t - 6)) * DFF + j0 + 4 * n) = g;
.LBB0_771:
	s_or_b64 exec, exec, s[22:23]
	v_mov_b32_e32 v155, v179
	v_mov_b32_e32 v159, v179
	v_mov_b32_e32 v160, v179
	v_mov_b32_e32 v161, v179
	v_mov_b32_e32 v162, v179
	v_mov_b32_e32 v163, v179
	v_mov_b32_e32 v167, v179
	v_mov_b32_e32 v168, v179
	v_mov_b32_dpp v155, v142 row_shr:1 row_mask:0xf bank_mask:0xf
	v_mov_b32_dpp v159, v142 row_shr:2 row_mask:0xf bank_mask:0xf
	v_mov_b32_dpp v160, v143 row_shr:1 row_mask:0xf bank_mask:0xf
	v_mov_b32_dpp v161, v143 row_shr:2 row_mask:0xf bank_mask:0xf
	v_mov_b32_dpp v162, v144 row_shr:1 row_mask:0xf bank_mask:0xf
	v_mov_b32_dpp v163, v144 row_shr:2 row_mask:0xf bank_mask:0xf
	v_mov_b32_dpp v167, v145 row_shr:1 row_mask:0xf bank_mask:0xf
	v_mov_b32_dpp v168, v145 row_shr:2 row_mask:0xf bank_mask:0xf
	s_waitcnt vmcnt(0)
	s_and_saveexec_b64 s[22:23], s[12:13]
	s_cbranch_execz .LBB0_773
	v_ashrrev_i32_e32 v157, 31, v156
	v_lshl_add_u64 v[156:157], v[156:157], 1, v[178:179]
	v_mov_b64_e32 v[190:191], s[62:63]
	v_mad_u64_u32 v[190:191], s[82:83], v156, s26, v[190:191]
	v_mad_i32_i24 v191, v157, s26, v191
	v_lshl_add_u64 v[156:157], v[184:185], 2, v[190:191]
	global_store_dwordx4 v[156:157], v[142:145], off
.LBB0_773:
	s_or_b64 exec, exec, s[22:23]
	v_cndmask_b32_e64 v146, v146, v150, s[8:9]
	v_cndmask_b32_e64 v147, v147, v151, s[8:9]
	v_cndmask_b32_e64 v148, v148, v152, s[8:9]
	v_cndmask_b32_e64 v149, v149, v153, s[8:9]
	v_cndmask_b32_e64 v156, v155, v150, s[10:11]
	v_cndmask_b32_e64 v146, v146, v159, s[6:7]
	v_cndmask_b32_e64 v150, v160, v151, s[10:11]
	v_cndmask_b32_e64 v147, v147, v161, s[6:7]
	v_cndmask_b32_e64 v151, v162, v152, s[10:11]
	v_cndmask_b32_e64 v148, v148, v163, s[6:7]
	v_cndmask_b32_e64 v152, v167, v153, s[10:11]
	v_cndmask_b32_e64 v149, v149, v168, s[6:7]
	s_mov_b64 s[22:23], 0

; __device__ __forceinline__ float dpp_shr1(float old, float src) { return __builtin_bit_cast(float, __builtin_amdgcn_update_dpp(__builtin_bit_cast(int, old), __builtin_bit_cast(int, src), 0x111, 0xf, 0xf, false)); }
; __device__ __forceinline__ float dpp_shr2(float old, float src) { return __builtin_bit_cast(float, __builtin_amdgcn_update_dpp(__builtin_bit_cast(int, old), __builtin_bit_cast(int, src), 0x112, 0xf, 0xf, false)); }
;     __device__ __forceinline__ void operator()(const f32x4 (&acc)[2][2][4][2], const Unit& u, int wr, int wc, int fr, int fq) const {
;     ...
;                         const int t = fr & 7, bs = (r - MP) >> 3; f32x4 s0 = (f32x4){0.f, 0.f, 0.f, 0.f}, s1 = s0;
;                         if (t < 2) { s0 = *(const f32x4*)(st_ffn + ((size_t)bs * 2 + 0) * DFF + j0 + 4 * n); s1 = *(const f32x4*)(st_ffn + ((size_t)bs * 2 + 1) * DFF + j0 + 4 * n); }
; #pragma unroll
;                         for (int e = 0; e < 4; ++e) { const float a1 = dpp_shr1(0.f, g[e]), a2 = dpp_shr2(0.f, g[e]); p1[e] = (t >= 1) ? a1 : s1[e]; p2[e] = (t >= 2) ? a2 : (t == 1 ? s1[e] : s0[e]); }
;                         if (t >= 6) *(f32x4*)(out + O_SFFN + ((size_t)bs * 2 + (t - 6)) * DFF + j0 + 4 * n) = g;
.LBB0_779:
	s_or_b64 exec, exec, s[22:23]
	v_mov_b32_e32 v117, v179
	v_mov_b32_e32 v148, v179
	v_mov_b32_e32 v149, v179
	v_mov_b32_e32 v150, v179
	v_mov_b32_e32 v151, v179
	v_mov_b32_e32 v153, v179
	v_mov_b32_e32 v154, v179
	v_mov_b32_e32 v155, v179
	v_mov_b32_dpp v117, v110 row_shr:1 row_mask:0xf bank_mask:0xf
	v_mov_b32_dpp v148, v110 row_shr:2 row_mask:0xf bank_mask:0xf
	v_mov_b32_dpp v149, v111 row_shr:1 row_mask:0xf bank_mask:0xf
	v_mov_b32_dpp v150, v111 row_shr:2 row_mask:0xf bank_mask:0xf
	v_mov_b32_dpp v151, v112 row_shr:1 row_mask:0xf bank_mask:0xf
	v_mov_b32_dpp v153, v112 row_shr:2 row_mask:0xf bank_mask:0xf
	v_mov_b32_dpp v154, v113 row_shr:1 row_mask:0xf bank_mask:0xf
	v_mov_b32_dpp v155, v113 row_shr:2 row_mask:0xf bank_mask:0xf
	s_waitcnt vmcnt(0)
	s_and_saveexec_b64 s[22:23], s[12:13]
	s_cbranch_execz .LBB0_781
	v_ashrrev_i32_e32 v147, 31, v146
	v_lshl_add_u64 v[146:147], v[146:147], 1, v[178:179]
	v_mov_b64_e32 v[156:157], s[62:63]
	v_mad_u64_u32 v[156:157], s[82:83], v146, s26, v[156:157]
	v_mad_i32_i24 v157, v147, s26, v157
	v_lshl_add_u64 v[146:147], v[184:185], 2, v[156:157]
	global_store_dwordx4 v[146:147], v[110:113], off
.LBB0_781:
	s_or_b64 exec, exec, s[22:23]
	v_cndmask_b32_e64 v146, v117, v142, s[10:11]
	v_cndmask_b32_e64 v117, v122, v142, s[8:9]
	v_cndmask_b32_e64 v122, v117, v148, s[6:7]
	v_cndmask_b32_e64 v117, v123, v143, s[8:9]
	v_cndmask_b32_e64 v123, v117, v150, s[6:7]
	v_cndmask_b32_e64 v117, v124, v144, s[8:9]
	v_cndmask_b32_e64 v124, v117, v153, s[6:7]
	v_cndmask_b32_e64 v117, v125, v145, s[8:9]
	v_cndmask_b32_e64 v142, v149, v143, s[10:11]
	v_cndmask_b32_e64 v143, v151, v144, s[10:11]
	v_cndmask_b32_e64 v144, v154, v145, s[10:11]
	v_cndmask_b32_e64 v125, v117, v155, s[6:7]
	s_mov_b64 s[22:23], 0

; __device__ __forceinline__ float dpp_shr1(float old, float src) { return __builtin_bit_cast(float, __builtin_amdgcn_update_dpp(__builtin_bit_cast(int, old), __builtin_bit_cast(int, src), 0x111, 0xf, 0xf, false)); }
; __device__ __forceinline__ float dpp_shr2(float old, float src) { return __builtin_bit_cast(float, __builtin_amdgcn_update_dpp(__builtin_bit_cast(int, old), __builtin_bit_cast(int, src), 0x112, 0xf, 0xf, false)); }
;     __device__ __forceinline__ void operator()(const f32x4 (&acc)[2][2][4][2], const Unit& u, int wr, int wc, int fr, int fq) const {
;     ...
;                         const int t = fr & 7, bs = (r - MP) >> 3; f32x4 s0 = (f32x4){0.f, 0.f, 0.f, 0.f}, s1 = s0;
;                         if (t < 2) { s0 = *(const f32x4*)(st_ffn + ((size_t)bs * 2 + 0) * DFF + j0 + 4 * n); s1 = *(const f32x4*)(st_ffn + ((size_t)bs * 2 + 1) * DFF + j0 + 4 * n); }
; #pragma unroll
;                         for (int e = 0; e < 4; ++e) { const float a1 = dpp_shr1(0.f, g[e]), a2 = dpp_shr2(0.f, g[e]); p1[e] = (t >= 1) ? a1 : s1[e]; p2[e] = (t >= 2) ? a2 : (t == 1 ? s1[e] : s0[e]); }
;                         if (t >= 6) *(f32x4*)(out + O_SFFN + ((size_t)bs * 2 + (t - 6)) * DFF + j0 + 4 * n) = g;
.LBB0_789:
	s_or_b64 exec, exec, s[80:81]
	v_mov_b32_e32 v113, v179
	v_mov_b32_e32 v155, v179
	v_mov_b32_e32 v156, v179
	v_mov_b32_e32 v157, v179
	v_mov_b32_e32 v159, v179
	v_mov_b32_e32 v160, v179
	v_mov_b32_e32 v161, v179
	v_mov_b32_e32 v162, v179
	v_mov_b32_dpp v113, v104 row_shr:1 row_mask:0xf bank_mask:0xf
	v_mov_b32_dpp v155, v104 row_shr:2 row_mask:0xf bank_mask:0xf
	v_mov_b32_dpp v156, v105 row_shr:1 row_mask:0xf bank_mask:0xf
	v_mov_b32_dpp v157, v105 row_shr:2 row_mask:0xf bank_mask:0xf
	v_mov_b32_dpp v159, v106 row_shr:1 row_mask:0xf bank_mask:0xf
	v_mov_b32_dpp v160, v106 row_shr:2 row_mask:0xf bank_mask:0xf
	v_mov_b32_dpp v161, v107 row_shr:1 row_mask:0xf bank_mask:0xf
	v_mov_b32_dpp v162, v107 row_shr:2 row_mask:0xf bank_mask:0xf
	s_waitcnt vmcnt(0)
	s_and_saveexec_b64 s[80:81], s[12:13]
	s_cbranch_execz .LBB0_791
	v_ashrrev_i32_e32 v117, 31, v116
	v_lshl_add_u64 v[116:117], v[116:117], 1, v[178:179]
	v_mov_b64_e32 v[168:169], s[62:63]
	v_mad_u64_u32 v[168:169], s[82:83], v116, s26, v[168:169]
	v_mad_i32_i24 v169, v117, s26, v169
	v_lshl_add_u64 v[116:117], v[184:185], 2, v[168:169]
	global_store_dwordx4 v[116:117], v[104:107], off
.LBB0_791:
	s_or_b64 exec, exec, s[80:81]
	v_cndmask_b32_e64 v154, v113, v146, s[10:11]
	v_cndmask_b32_e64 v113, v142, v146, s[8:9]
	v_cndmask_b32_e64 v116, v113, v155, s[6:7]
	v_cndmask_b32_e64 v113, v143, v147, s[8:9]
	v_cndmask_b32_e64 v117, v113, v157, s[6:7]
	v_cndmask_b32_e64 v113, v144, v148, s[8:9]
	v_cndmask_b32_e64 v143, v113, v160, s[6:7]
	v_cndmask_b32_e64 v113, v145, v149, s[8:9]
	v_cndmask_b32_e64 v142, v156, v147, s[10:11]
	v_cndmask_b32_e64 v146, v159, v148, s[10:11]
	v_cndmask_b32_e64 v147, v161, v149, s[10:11]
	v_cndmask_b32_e64 v144, v113, v162, s[6:7]
	s_mov_b64 s[80:81], 0

; __device__ __forceinline__ float dpp_shr1(float old, float src) { return __builtin_bit_cast(float, __builtin_amdgcn_update_dpp(__builtin_bit_cast(int, old), __builtin_bit_cast(int, src), 0x111, 0xf, 0xf, false)); }
; __device__ __forceinline__ float dpp_shr2(float old, float src) { return __builtin_bit_cast(float, __builtin_amdgcn_update_dpp(__builtin_bit_cast(int, old), __builtin_bit_cast(int, src), 0x112, 0xf, 0xf, false)); }
;     __device__ __forceinline__ void operator()(const f32x4 (&acc)[2][2][4][2], const Unit& u, int wr, int wc, int fr, int fq) const {
;     ...
;                         const int t = fr & 7, bs = (r - MP) >> 3; f32x4 s0 = (f32x4){0.f, 0.f, 0.f, 0.f}, s1 = s0;
;                         if (t < 2) { s0 = *(const f32x4*)(st_ffn + ((size_t)bs * 2 + 0) * DFF + j0 + 4 * n); s1 = *(const f32x4*)(st_ffn + ((size_t)bs * 2 + 1) * DFF + j0 + 4 * n); }
; #pragma unroll
;                         for (int e = 0; e < 4; ++e) { const float a1 = dpp_shr1(0.f, g[e]), a2 = dpp_shr2(0.f, g[e]); p1[e] = (t >= 1) ? a1 : s1[e]; p2[e] = (t >= 2) ? a2 : (t == 1 ? s1[e] : s0[e]); }
;                         if (t >= 6) *(f32x4*)(out + O_SFFN + ((size_t)bs * 2 + (t - 6)) * DFF + j0 + 4 * n) = g;
.LBB0_797:
	s_or_b64 exec, exec, s[80:81]
	v_mov_b32_e32 v101, v179
	v_mov_b32_e32 v116, v179
	v_mov_b32_e32 v117, v179
	v_mov_b32_e32 v143, v179
	v_mov_b32_e32 v144, v179
	v_mov_b32_e32 v145, v179
	v_mov_b32_e32 v146, v179
	v_mov_b32_e32 v147, v179
	v_mov_b32_dpp v101, v104 row_shr:1 row_mask:0xf bank_mask:0xf
	v_mov_b32_dpp v116, v104 row_shr:2 row_mask:0xf bank_mask:0xf
	v_mov_b32_dpp v117, v105 row_shr:1 row_mask:0xf bank_mask:0xf
	v_mov_b32_dpp v143, v105 row_shr:2 row_mask:0xf bank_mask:0xf
	v_mov_b32_dpp v144, v106 row_shr:1 row_mask:0xf bank_mask:0xf
	v_mov_b32_dpp v145, v106 row_shr:2 row_mask:0xf bank_mask:0xf
	v_mov_b32_dpp v146, v107 row_shr:1 row_mask:0xf bank_mask:0xf
	v_mov_b32_dpp v147, v107 row_shr:2 row_mask:0xf bank_mask:0xf
	s_waitcnt vmcnt(0)
	s_and_saveexec_b64 s[80:81], s[12:13]
	s_cbranch_execz .LBB0_799
	v_ashrrev_i32_e32 v113, 31, v112
	v_lshl_add_u64 v[112:113], v[112:113], 1, v[178:179]
	v_mov_b64_e32 v[148:149], s[62:63]
	v_mad_u64_u32 v[148:149], s[82:83], v112, s26, v[148:149]
	v_mad_i32_i24 v149, v113, s26, v149
	v_lshl_add_u64 v[112:113], v[184:185], 2, v[148:149]
	global_store_dwordx4 v[112:113], v[104:107], off
.LBB0_799:
	s_or_b64 exec, exec, s[80:81]
	v_cndmask_b32_e64 v112, v101, v122, s[10:11]
	v_cndmask_b32_e64 v101, v108, v122, s[8:9]
	v_cndmask_b32_e64 v108, v101, v116, s[6:7]
	v_cndmask_b32_e64 v101, v109, v123, s[8:9]
	v_cndmask_b32_e64 v109, v101, v143, s[6:7]
	v_cndmask_b32_e64 v101, v110, v124, s[8:9]
	v_cndmask_b32_e64 v110, v101, v145, s[6:7]
	v_cndmask_b32_e64 v101, v111, v125, s[8:9]
	v_cndmask_b32_e64 v113, v117, v123, s[10:11]
	v_cndmask_b32_e64 v116, v144, v124, s[10:11]
	v_cndmask_b32_e64 v117, v146, v125, s[10:11]
	v_cndmask_b32_e64 v111, v101, v147, s[6:7]
	s_mov_b64 s[80:81], 0

; __device__ __forceinline__ float dpp_shr1(float old, float src) { return __builtin_bit_cast(float, __builtin_amdgcn_update_dpp(__builtin_bit_cast(int, old), __builtin_bit_cast(int, src), 0x111, 0xf, 0xf, false)); }
; __device__ __forceinline__ float dpp_shr2(float old, float src) { return __builtin_bit_cast(float, __builtin_amdgcn_update_dpp(__builtin_bit_cast(int, old), __builtin_bit_cast(int, src), 0x112, 0xf, 0xf, false)); }
;     __device__ __forceinline__ void operator()(const f32x4 (&acc)[2][2][4][2], const Unit& u, int wr, int wc, int fr, int fq) const {
;     ...
;                         const int t = fr & 7, bs = (r - MP) >> 3; f32x4 s0 = (f32x4){0.f, 0.f, 0.f, 0.f}, s1 = s0;
;                         if (t < 2) { s0 = *(const f32x4*)(st_ffn + ((size_t)bs * 2 + 0) * DFF + j0 + 4 * n); s1 = *(const f32x4*)(st_ffn + ((size_t)bs * 2 + 1) * DFF + j0 + 4 * n); }
; #pragma unroll
;                         for (int e = 0; e < 4; ++e) { const float a1 = dpp_shr1(0.f, g[e]), a2 = dpp_shr2(0.f, g[e]); p1[e] = (t >= 1) ? a1 : s1[e]; p2[e] = (t >= 2) ? a2 : (t == 1 ? s1[e] : s0[e]); }
;                         if (t >= 6) *(f32x4*)(out + O_SFFN + ((size_t)bs * 2 + (t - 6)) * DFF + j0 + 4 * n) = g;
.LBB0_805:
	s_or_b64 exec, exec, s[80:81]
	v_mov_b32_e32 v97, v179
	v_mov_b32_e32 v112, v179
	v_mov_b32_e32 v116, v179
	v_mov_b32_e32 v117, v179
	v_mov_b32_e32 v122, v179
	v_mov_b32_e32 v123, v179
	v_mov_b32_e32 v124, v179
	v_mov_b32_e32 v125, v179
	v_mov_b32_dpp v97, v92 row_shr:1 row_mask:0xf bank_mask:0xf
	v_mov_b32_dpp v112, v92 row_shr:2 row_mask:0xf bank_mask:0xf
	v_mov_b32_dpp v116, v93 row_shr:1 row_mask:0xf bank_mask:0xf
	v_mov_b32_dpp v117, v93 row_shr:2 row_mask:0xf bank_mask:0xf
	v_mov_b32_dpp v122, v94 row_shr:1 row_mask:0xf bank_mask:0xf
	v_mov_b32_dpp v123, v94 row_shr:2 row_mask:0xf bank_mask:0xf
	v_mov_b32_dpp v124, v95 row_shr:1 row_mask:0xf bank_mask:0xf
	v_mov_b32_dpp v125, v95 row_shr:2 row_mask:0xf bank_mask:0xf
	s_waitcnt vmcnt(0)
	s_and_saveexec_b64 s[80:81], s[12:13]
	s_cbranch_execz .LBB0_807
	v_ashrrev_i32_e32 v101, 31, v100
	v_lshl_add_u64 v[100:101], v[100:101], 1, v[178:179]
	v_mov_b64_e32 v[144:145], s[62:63]
	v_mad_u64_u32 v[144:145], s[82:83], v100, s26, v[144:145]
	v_mad_i32_i24 v145, v101, s26, v145
	v_lshl_add_u64 v[100:101], v[184:185], 2, v[144:145]
	global_store_dwordx4 v[100:101], v[92:95], off
.LBB0_807:
	s_or_b64 exec, exec, s[80:81]
	v_cndmask_b32_e64 v100, v97, v108, s[10:11]
	v_cndmask_b32_e64 v97, v104, v108, s[8:9]
	v_cndmask_b32_e64 v101, v97, v112, s[6:7]
	v_cndmask_b32_e64 v97, v105, v109, s[8:9]
	v_cndmask_b32_e64 v105, v97, v117, s[6:7]
	v_cndmask_b32_e64 v97, v106, v110, s[8:9]
	v_cndmask_b32_e64 v106, v97, v123, s[6:7]
	v_cndmask_b32_e64 v97, v107, v111, s[8:9]
	v_cndmask_b32_e64 v104, v116, v109, s[10:11]
	v_cndmask_b32_e64 v108, v122, v110, s[10:11]
	v_cndmask_b32_e64 v109, v124, v111, s[10:11]
	v_cndmask_b32_e64 v107, v97, v125, s[6:7]
	s_mov_b64 s[80:81], 0

; __device__ __forceinline__ float dpp_shr1(float old, float src) { return __builtin_bit_cast(float, __builtin_amdgcn_update_dpp(__builtin_bit_cast(int, old), __builtin_bit_cast(int, src), 0x111, 0xf, 0xf, false)); }
; __device__ __forceinline__ float dpp_shr2(float old, float src) { return __builtin_bit_cast(float, __builtin_amdgcn_update_dpp(__builtin_bit_cast(int, old), __builtin_bit_cast(int, src), 0x112, 0xf, 0xf, false)); }
;     __device__ __forceinline__ void operator()(const f32x4 (&acc)[2][2][4][2], const Unit& u, int wr, int wc, int fr, int fq) const {
;     ...
;                         const int t = fr & 7, bs = (r - MP) >> 3; f32x4 s0 = (f32x4){0.f, 0.f, 0.f, 0.f}, s1 = s0;
;                         if (t < 2) { s0 = *(const f32x4*)(st_ffn + ((size_t)bs * 2 + 0) * DFF + j0 + 4 * n); s1 = *(const f32x4*)(st_ffn + ((size_t)bs * 2 + 1) * DFF + j0 + 4 * n); }
; #pragma unroll
;                         for (int e = 0; e < 4; ++e) { const float a1 = dpp_shr1(0.f, g[e]), a2 = dpp_shr2(0.f, g[e]); p1[e] = (t >= 1) ? a1 : s1[e]; p2[e] = (t >= 2) ? a2 : (t == 1 ? s1[e] : s0[e]); }
;                         if (t >= 6) *(f32x4*)(out + O_SFFN + ((size_t)bs * 2 + (t - 6)) * DFF + j0 + 4 * n) = g;
.LBB0_813:
	s_or_b64 exec, exec, s[80:81]
	v_mov_b32_e32 v89, v179
	v_mov_b32_e32 v100, v179
	v_mov_b32_e32 v101, v179
	v_mov_b32_e32 v104, v179
	v_mov_b32_e32 v105, v179
	v_mov_b32_e32 v106, v179
	v_mov_b32_e32 v107, v179
	v_mov_b32_e32 v108, v179
	v_mov_b32_dpp v89, v78 row_shr:1 row_mask:0xf bank_mask:0xf
	v_mov_b32_dpp v100, v78 row_shr:2 row_mask:0xf bank_mask:0xf
	v_mov_b32_dpp v101, v79 row_shr:1 row_mask:0xf bank_mask:0xf
	v_mov_b32_dpp v104, v79 row_shr:2 row_mask:0xf bank_mask:0xf
	v_mov_b32_dpp v105, v80 row_shr:1 row_mask:0xf bank_mask:0xf
	v_mov_b32_dpp v106, v80 row_shr:2 row_mask:0xf bank_mask:0xf
	v_mov_b32_dpp v107, v81 row_shr:1 row_mask:0xf bank_mask:0xf
	v_mov_b32_dpp v108, v81 row_shr:2 row_mask:0xf bank_mask:0xf
	s_waitcnt vmcnt(0)
	s_and_saveexec_b64 s[80:81], s[12:13]
	s_cbranch_execz .LBB0_815
	v_ashrrev_i32_e32 v97, 31, v96
	v_lshl_add_u64 v[96:97], v[96:97], 1, v[178:179]
	v_mov_b64_e32 v[110:111], s[62:63]
	v_mad_u64_u32 v[110:111], s[82:83], v96, s26, v[110:111]
	v_mad_i32_i24 v111, v97, s26, v111
	v_lshl_add_u64 v[96:97], v[184:185], 2, v[110:111]
	global_store_dwordx4 v[96:97], v[78:81], off
.LBB0_815:
	s_or_b64 exec, exec, s[80:81]
	v_cndmask_b32_e64 v84, v84, v92, s[8:9]
	v_cndmask_b32_e64 v85, v85, v93, s[8:9]
	v_cndmask_b32_e64 v86, v86, v94, s[8:9]
	v_cndmask_b32_e64 v87, v87, v95, s[8:9]
	v_cndmask_b32_e64 v96, v89, v92, s[10:11]
	v_cndmask_b32_e64 v84, v84, v100, s[6:7]
	v_cndmask_b32_e64 v92, v101, v93, s[10:11]
	v_cndmask_b32_e64 v85, v85, v104, s[6:7]
	v_cndmask_b32_e64 v93, v105, v94, s[10:11]
	v_cndmask_b32_e64 v86, v86, v106, s[6:7]
	v_cndmask_b32_e64 v94, v107, v95, s[10:11]
	v_cndmask_b32_e64 v87, v87, v108, s[6:7]
	s_mov_b64 s[80:81], 0

; __device__ __forceinline__ float dpp_shr1(float old, float src) { return __builtin_bit_cast(float, __builtin_amdgcn_update_dpp(__builtin_bit_cast(int, old), __builtin_bit_cast(int, src), 0x111, 0xf, 0xf, false)); }
; __device__ __forceinline__ float dpp_shr2(float old, float src) { return __builtin_bit_cast(float, __builtin_amdgcn_update_dpp(__builtin_bit_cast(int, old), __builtin_bit_cast(int, src), 0x112, 0xf, 0xf, false)); }
;     __device__ __forceinline__ void operator()(const f32x4 (&acc)[2][2][4][2], const Unit& u, int wr, int wc, int fr, int fq) const {
;     ...
;                         const int t = fr & 7, bs = (r - MP) >> 3; f32x4 s0 = (f32x4){0.f, 0.f, 0.f, 0.f}, s1 = s0;
;                         if (t < 2) { s0 = *(const f32x4*)(st_ffn + ((size_t)bs * 2 + 0) * DFF + j0 + 4 * n); s1 = *(const f32x4*)(st_ffn + ((size_t)bs * 2 + 1) * DFF + j0 + 4 * n); }
; #pragma unroll
;                         for (int e = 0; e < 4; ++e) { const float a1 = dpp_shr1(0.f, g[e]), a2 = dpp_shr2(0.f, g[e]); p1[e] = (t >= 1) ? a1 : s1[e]; p2[e] = (t >= 2) ? a2 : (t == 1 ? s1[e] : s0[e]); }
;                         if (t >= 6) *(f32x4*)(out + O_SFFN + ((size_t)bs * 2 + (t - 6)) * DFF + j0 + 4 * n) = g;
.LBB0_837:
	s_or_b64 exec, exec, s[20:21]
	v_mov_b32_e32 v101, v179
	v_mov_b32_e32 v111, v179
	v_mov_b32_e32 v116, v179
	v_mov_b32_e32 v117, v179
	v_mov_b32_e32 v120, v179
	v_mov_b32_e32 v121, v179
	v_mov_b32_e32 v122, v179
	v_mov_b32_e32 v85, v179
	v_mov_b32_dpp v101, v66 row_shr:1 row_mask:0xf bank_mask:0xf
	v_mov_b32_dpp v111, v66 row_shr:2 row_mask:0xf bank_mask:0xf
	v_mov_b32_dpp v116, v67 row_shr:1 row_mask:0xf bank_mask:0xf
	v_mov_b32_dpp v117, v67 row_shr:2 row_mask:0xf bank_mask:0xf
	v_mov_b32_dpp v120, v68 row_shr:1 row_mask:0xf bank_mask:0xf
	v_mov_b32_dpp v121, v68 row_shr:2 row_mask:0xf bank_mask:0xf
	v_mov_b32_dpp v122, v69 row_shr:1 row_mask:0xf bank_mask:0xf
	v_mov_b32_dpp v85, v69 row_shr:2 row_mask:0xf bank_mask:0xf
	s_waitcnt vmcnt(0)
	s_and_saveexec_b64 s[20:21], s[12:13]
	s_cbranch_execz .LBB0_839
	v_ashrrev_i32_e32 v93, 31, v92
	v_lshl_add_u64 v[92:93], v[92:93], 1, v[178:179]
	v_mov_b64_e32 v[126:127], s[34:35]
	v_mad_u64_u32 v[126:127], s[76:77], v92, s26, v[126:127]
	v_mad_i32_i24 v127, v93, s26, v127
	v_lshl_add_u64 v[92:93], v[184:185], 2, v[126:127]
	v_add_co_u32_e32 v92, vcc, 0x15c86000, v92
	s_nop 1
	v_addc_co_u32_e32 v93, vcc, 0, v93, vcc
	global_store_dwordx4 v[92:93], v[66:69], off offset:16
.LBB0_839:
	s_or_b64 exec, exec, s[20:21]
	v_cndmask_b32_e64 v93, v94, v104, s[8:9]
	v_cndmask_b32_e64 v94, v95, v105, s[8:9]
	v_cndmask_b32_e64 v95, v96, v106, s[8:9]
	v_cndmask_b32_e64 v97, v97, v107, s[8:9]
	v_cndmask_b32_e64 v92, v101, v104, s[10:11]
	v_cndmask_b32_e64 v101, v93, v111, s[6:7]
	v_cndmask_b32_e64 v93, v116, v105, s[10:11]
	v_cndmask_b32_e64 v104, v94, v117, s[6:7]
	v_cndmask_b32_e64 v94, v120, v106, s[10:11]
	v_cndmask_b32_e64 v96, v95, v121, s[6:7]
	v_cndmask_b32_e64 v95, v122, v107, s[10:11]
	v_cndmask_b32_e64 v97, v97, v85, s[6:7]
	s_mov_b64 s[20:21], 0

; __device__ __forceinline__ float dpp_shr1(float old, float src) { return __builtin_bit_cast(float, __builtin_amdgcn_update_dpp(__builtin_bit_cast(int, old), __builtin_bit_cast(int, src), 0x111, 0xf, 0xf, false)); }
; __device__ __forceinline__ float dpp_shr2(float old, float src) { return __builtin_bit_cast(float, __builtin_amdgcn_update_dpp(__builtin_bit_cast(int, old), __builtin_bit_cast(int, src), 0x112, 0xf, 0xf, false)); }
;     __device__ __forceinline__ void operator()(const f32x4 (&acc)[2][2][4][2], const Unit& u, int wr, int wc, int fr, int fq) const {
;     ...
;                         const int t = fr & 7, bs = (r - MP) >> 3; f32x4 s0 = (f32x4){0.f, 0.f, 0.f, 0.f}, s1 = s0;
;                         if (t < 2) { s0 = *(const f32x4*)(st_ffn + ((size_t)bs * 2 + 0) * DFF + j0 + 4 * n); s1 = *(const f32x4*)(st_ffn + ((size_t)bs * 2 + 1) * DFF + j0 + 4 * n); }
; #pragma unroll
;                         for (int e = 0; e < 4; ++e) { const float a1 = dpp_shr1(0.f, g[e]), a2 = dpp_shr2(0.f, g[e]); p1[e] = (t >= 1) ? a1 : s1[e]; p2[e] = (t >= 2) ? a2 : (t == 1 ? s1[e] : s0[e]); }
;                         if (t >= 6) *(f32x4*)(out + O_SFFN + ((size_t)bs * 2 + (t - 6)) * DFF + j0 + 4 * n) = g;
.LBB0_845:
	s_or_b64 exec, exec, s[20:21]
	v_mov_b32_e32 v85, v179
	v_mov_b32_e32 v96, v179
	v_mov_b32_e32 v97, v179
	v_mov_b32_e32 v100, v179
	v_mov_b32_e32 v101, v179
	v_mov_b32_e32 v104, v179
	v_mov_b32_e32 v105, v179
	v_mov_b32_e32 v69, v179
	v_mov_b32_dpp v85, v58 row_shr:1 row_mask:0xf bank_mask:0xf
	v_mov_b32_dpp v96, v58 row_shr:2 row_mask:0xf bank_mask:0xf
	v_mov_b32_dpp v97, v59 row_shr:1 row_mask:0xf bank_mask:0xf
	v_mov_b32_dpp v100, v59 row_shr:2 row_mask:0xf bank_mask:0xf
	v_mov_b32_dpp v101, v60 row_shr:1 row_mask:0xf bank_mask:0xf
	v_mov_b32_dpp v104, v60 row_shr:2 row_mask:0xf bank_mask:0xf
	v_mov_b32_dpp v105, v61 row_shr:1 row_mask:0xf bank_mask:0xf
	v_mov_b32_dpp v69, v61 row_shr:2 row_mask:0xf bank_mask:0xf
	s_waitcnt vmcnt(0)
	s_and_saveexec_b64 s[20:21], s[12:13]
	s_cbranch_execz .LBB0_847
	v_ashrrev_i32_e32 v63, 31, v62
	v_lshl_add_u64 v[62:63], v[62:63], 1, v[178:179]
	v_mov_b64_e32 v[106:107], s[34:35]
	v_mad_u64_u32 v[106:107], s[76:77], v62, s26, v[106:107]
	v_mad_i32_i24 v107, v63, s26, v107
	v_lshl_add_u64 v[62:63], v[184:185], 2, v[106:107]
	v_add_co_u32_e32 v62, vcc, 0x15c86000, v62
	s_nop 1
	v_addc_co_u32_e32 v63, vcc, 0, v63, vcc
	global_store_dwordx4 v[62:63], v[58:61], off offset:16
.LBB0_847:
	s_or_b64 exec, exec, s[20:21]
	v_cndmask_b32_e64 v63, v64, v92, s[8:9]
	v_cndmask_b32_e64 v64, v65, v93, s[8:9]
	v_cndmask_b32_e64 v65, v66, v94, s[8:9]
	v_cndmask_b32_e64 v67, v67, v95, s[8:9]
	v_cndmask_b32_e64 v62, v85, v92, s[10:11]
	v_cndmask_b32_e64 v85, v63, v96, s[6:7]
	v_cndmask_b32_e64 v63, v97, v93, s[10:11]
	v_cndmask_b32_e64 v92, v64, v100, s[6:7]
	v_cndmask_b32_e64 v64, v101, v94, s[10:11]
	v_cndmask_b32_e64 v66, v65, v104, s[6:7]
	v_cndmask_b32_e64 v65, v105, v95, s[10:11]
	v_cndmask_b32_e64 v67, v67, v69, s[6:7]
	s_mov_b64 s[20:21], 0

; __device__ __forceinline__ float dpp_shr1(float old, float src) { return __builtin_bit_cast(float, __builtin_amdgcn_update_dpp(__builtin_bit_cast(int, old), __builtin_bit_cast(int, src), 0x111, 0xf, 0xf, false)); }
; __device__ __forceinline__ float dpp_shr2(float old, float src) { return __builtin_bit_cast(float, __builtin_amdgcn_update_dpp(__builtin_bit_cast(int, old), __builtin_bit_cast(int, src), 0x112, 0xf, 0xf, false)); }
;     __device__ __forceinline__ void operator()(const f32x4 (&acc)[2][2][4][2], const Unit& u, int wr, int wc, int fr, int fq) const {
;     ...
;                         const int t = fr & 7, bs = (r - MP) >> 3; f32x4 s0 = (f32x4){0.f, 0.f, 0.f, 0.f}, s1 = s0;
;                         if (t < 2) { s0 = *(const f32x4*)(st_ffn + ((size_t)bs * 2 + 0) * DFF + j0 + 4 * n); s1 = *(const f32x4*)(st_ffn + ((size_t)bs * 2 + 1) * DFF + j0 + 4 * n); }
; #pragma unroll
;                         for (int e = 0; e < 4; ++e) { const float a1 = dpp_shr1(0.f, g[e]), a2 = dpp_shr2(0.f, g[e]); p1[e] = (t >= 1) ? a1 : s1[e]; p2[e] = (t >= 2) ? a2 : (t == 1 ? s1[e] : s0[e]); }
;                         if (t >= 6) *(f32x4*)(out + O_SFFN + ((size_t)bs * 2 + (t - 6)) * DFF + j0 + 4 * n) = g;
.LBB0_853:
	s_or_b64 exec, exec, s[20:21]
	v_mov_b32_e32 v63, v179
	v_mov_b32_e32 v64, v179
	v_mov_b32_e32 v65, v179
	v_mov_b32_e32 v66, v179
	v_mov_b32_e32 v67, v179
	v_mov_b32_e32 v68, v179
	v_mov_b32_e32 v69, v179
	v_mov_b32_e32 v61, v179
	v_mov_b32_dpp v63, v46 row_shr:1 row_mask:0xf bank_mask:0xf
	v_mov_b32_dpp v64, v46 row_shr:2 row_mask:0xf bank_mask:0xf
	v_mov_b32_dpp v65, v47 row_shr:1 row_mask:0xf bank_mask:0xf
	v_mov_b32_dpp v66, v47 row_shr:2 row_mask:0xf bank_mask:0xf
	v_mov_b32_dpp v67, v48 row_shr:1 row_mask:0xf bank_mask:0xf
	v_mov_b32_dpp v68, v48 row_shr:2 row_mask:0xf bank_mask:0xf
	v_mov_b32_dpp v69, v49 row_shr:1 row_mask:0xf bank_mask:0xf
	v_mov_b32_dpp v61, v49 row_shr:2 row_mask:0xf bank_mask:0xf
	s_waitcnt vmcnt(0)
	s_and_saveexec_b64 s[20:21], s[12:13]
	s_cbranch_execz .LBB0_855
	v_ashrrev_i32_e32 v51, 31, v50
	v_lshl_add_u64 v[50:51], v[50:51], 1, v[178:179]
	v_mov_b64_e32 v[84:85], s[34:35]
	v_mad_u64_u32 v[84:85], s[76:77], v50, s26, v[84:85]
	v_mad_i32_i24 v85, v51, s26, v85
	v_lshl_add_u64 v[50:51], v[184:185], 2, v[84:85]
	v_add_co_u32_e32 v50, vcc, 0x15c86000, v50
	s_nop 1
	v_addc_co_u32_e32 v51, vcc, 0, v51, vcc
	global_store_dwordx4 v[50:51], v[46:49], off offset:16
.LBB0_855:
	s_or_b64 exec, exec, s[20:21]
	v_cndmask_b32_e64 v51, v52, v56, s[8:9]
	v_cndmask_b32_e64 v52, v53, v57, s[8:9]
	v_cndmask_b32_e64 v53, v54, v58, s[8:9]
	v_cndmask_b32_e64 v55, v55, v59, s[8:9]
	v_cndmask_b32_e64 v50, v63, v56, s[10:11]
	v_cndmask_b32_e64 v56, v51, v64, s[6:7]
	v_cndmask_b32_e64 v51, v65, v57, s[10:11]
	v_cndmask_b32_e64 v57, v52, v66, s[6:7]
	v_cndmask_b32_e64 v52, v67, v58, s[10:11]
	v_cndmask_b32_e64 v54, v53, v68, s[6:7]
	v_cndmask_b32_e64 v53, v69, v59, s[10:11]
	v_cndmask_b32_e64 v55, v55, v61, s[6:7]
	s_mov_b64 s[20:21], 0

; __device__ __forceinline__ float dpp_shr1(float old, float src) { return __builtin_bit_cast(float, __builtin_amdgcn_update_dpp(__builtin_bit_cast(int, old), __builtin_bit_cast(int, src), 0x111, 0xf, 0xf, false)); }
; __device__ __forceinline__ float dpp_shr2(float old, float src) { return __builtin_bit_cast(float, __builtin_amdgcn_update_dpp(__builtin_bit_cast(int, old), __builtin_bit_cast(int, src), 0x112, 0xf, 0xf, false)); }
;     __device__ __forceinline__ void operator()(const f32x4 (&acc)[2][2][4][2], const Unit& u, int wr, int wc, int fr, int fq) const {
;     ...
;                         const int t = fr & 7, bs = (r - MP) >> 3; f32x4 s0 = (f32x4){0.f, 0.f, 0.f, 0.f}, s1 = s0;
;                         if (t < 2) { s0 = *(const f32x4*)(st_ffn + ((size_t)bs * 2 + 0) * DFF + j0 + 4 * n); s1 = *(const f32x4*)(st_ffn + ((size_t)bs * 2 + 1) * DFF + j0 + 4 * n); }
; #pragma unroll
;                         for (int e = 0; e < 4; ++e) { const float a1 = dpp_shr1(0.f, g[e]), a2 = dpp_shr2(0.f, g[e]); p1[e] = (t >= 1) ? a1 : s1[e]; p2[e] = (t >= 2) ? a2 : (t == 1 ? s1[e] : s0[e]); }
;                         if (t >= 6) *(f32x4*)(out + O_SFFN + ((size_t)bs * 2 + (t - 6)) * DFF + j0 + 4 * n) = g;
.LBB0_863:
	s_or_b64 exec, exec, s[20:21]
	v_mov_b32_e32 v63, v179
	v_mov_b32_e32 v64, v179
	v_mov_b32_e32 v65, v179
	v_mov_b32_e32 v66, v179
	v_mov_b32_e32 v67, v179
	v_mov_b32_e32 v68, v179
	v_mov_b32_e32 v69, v179
	v_mov_b32_e32 v61, v179
	v_mov_b32_dpp v63, v38 row_shr:1 row_mask:0xf bank_mask:0xf
	v_mov_b32_dpp v64, v38 row_shr:2 row_mask:0xf bank_mask:0xf
	v_mov_b32_dpp v65, v39 row_shr:1 row_mask:0xf bank_mask:0xf
	v_mov_b32_dpp v66, v39 row_shr:2 row_mask:0xf bank_mask:0xf
	v_mov_b32_dpp v67, v40 row_shr:1 row_mask:0xf bank_mask:0xf
	v_mov_b32_dpp v68, v40 row_shr:2 row_mask:0xf bank_mask:0xf
	v_mov_b32_dpp v69, v41 row_shr:1 row_mask:0xf bank_mask:0xf
	v_mov_b32_dpp v61, v41 row_shr:2 row_mask:0xf bank_mask:0xf
	s_waitcnt vmcnt(0)
	s_and_saveexec_b64 s[20:21], s[12:13]
	s_cbranch_execz .LBB0_865
	v_ashrrev_i32_e32 v51, 31, v50
	v_lshl_add_u64 v[50:51], v[50:51], 1, v[178:179]
	v_mov_b64_e32 v[84:85], s[34:35]
	v_mad_u64_u32 v[84:85], s[22:23], v50, s26, v[84:85]
	v_mad_i32_i24 v85, v51, s26, v85
	v_lshl_add_u64 v[50:51], v[184:185], 2, v[84:85]
	v_add_co_u32_e32 v50, vcc, 0x15c86000, v50
	s_nop 1
	v_addc_co_u32_e32 v51, vcc, 0, v51, vcc
	global_store_dwordx4 v[50:51], v[38:41], off offset:16

; __device__ __forceinline__ float dpp_shr1(float old, float src) { return __builtin_bit_cast(float, __builtin_amdgcn_update_dpp(__builtin_bit_cast(int, old), __builtin_bit_cast(int, src), 0x111, 0xf, 0xf, false)); }
; __device__ __forceinline__ float dpp_shr2(float old, float src) { return __builtin_bit_cast(float, __builtin_amdgcn_update_dpp(__builtin_bit_cast(int, old), __builtin_bit_cast(int, src), 0x112, 0xf, 0xf, false)); }
;     __device__ __forceinline__ void operator()(const f32x4 (&acc)[2][2][4][2], const Unit& u, int wr, int wc, int fr, int fq) const {
;     ...
;                         const int t = fr & 7, bs = (r - MP) >> 3; f32x4 s0 = (f32x4){0.f, 0.f, 0.f, 0.f}, s1 = s0;
;                         if (t < 2) { s0 = *(const f32x4*)(st_ffn + ((size_t)bs * 2 + 0) * DFF + j0 + 4 * n); s1 = *(const f32x4*)(st_ffn + ((size_t)bs * 2 + 1) * DFF + j0 + 4 * n); }
; #pragma unroll
;                         for (int e = 0; e < 4; ++e) { const float a1 = dpp_shr1(0.f, g[e]), a2 = dpp_shr2(0.f, g[e]); p1[e] = (t >= 1) ? a1 : s1[e]; p2[e] = (t >= 2) ? a2 : (t == 1 ? s1[e] : s0[e]); }
;                         if (t >= 6) *(f32x4*)(out + O_SFFN + ((size_t)bs * 2 + (t - 6)) * DFF + j0 + 4 * n) = g;
.LBB0_871:
	s_or_b64 exec, exec, s[18:19]
	v_mov_b32_e32 v51, v179
	v_mov_b32_e32 v52, v179
	v_mov_b32_e32 v53, v179
	v_mov_b32_e32 v54, v179
	v_mov_b32_e32 v55, v179
	v_mov_b32_e32 v56, v179
	v_mov_b32_e32 v57, v179
	v_mov_b32_e32 v49, v179
	v_mov_b32_dpp v51, v34 row_shr:1 row_mask:0xf bank_mask:0xf
	v_mov_b32_dpp v52, v34 row_shr:2 row_mask:0xf bank_mask:0xf
	v_mov_b32_dpp v53, v35 row_shr:1 row_mask:0xf bank_mask:0xf
	v_mov_b32_dpp v54, v35 row_shr:2 row_mask:0xf bank_mask:0xf
	v_mov_b32_dpp v55, v36 row_shr:1 row_mask:0xf bank_mask:0xf
	v_mov_b32_dpp v56, v36 row_shr:2 row_mask:0xf bank_mask:0xf
	v_mov_b32_dpp v57, v37 row_shr:1 row_mask:0xf bank_mask:0xf
	v_mov_b32_dpp v49, v37 row_shr:2 row_mask:0xf bank_mask:0xf
	s_waitcnt vmcnt(0)
	s_and_saveexec_b64 s[18:19], s[12:13]
	s_cbranch_execz .LBB0_873
	v_ashrrev_i32_e32 v39, 31, v38
	v_lshl_add_u64 v[38:39], v[38:39], 1, v[178:179]
	v_mov_b64_e32 v[58:59], s[34:35]
	v_mad_u64_u32 v[58:59], s[20:21], v38, s26, v[58:59]
	v_mad_i32_i24 v59, v39, s26, v59
	v_lshl_add_u64 v[38:39], v[184:185], 2, v[58:59]
	v_add_co_u32_e32 v38, vcc, 0x15c86000, v38
	s_nop 1
	v_addc_co_u32_e32 v39, vcc, 0, v39, vcc
	global_store_dwordx4 v[38:39], v[34:37], off offset:16
.LBB0_873:
	s_or_b64 exec, exec, s[18:19]
	v_cndmask_b32_e64 v39, v40, v44, s[8:9]
	v_cndmask_b32_e64 v40, v41, v45, s[8:9]
	v_cndmask_b32_e64 v41, v42, v46, s[8:9]
	v_cndmask_b32_e64 v43, v43, v47, s[8:9]
	v_cndmask_b32_e64 v38, v51, v44, s[10:11]
	v_cndmask_b32_e64 v44, v39, v52, s[6:7]
	v_cndmask_b32_e64 v39, v53, v45, s[10:11]
	v_cndmask_b32_e64 v45, v40, v54, s[6:7]
	v_cndmask_b32_e64 v40, v55, v46, s[10:11]
	v_cndmask_b32_e64 v42, v41, v56, s[6:7]
	v_cndmask_b32_e64 v41, v57, v47, s[10:11]
	v_cndmask_b32_e64 v43, v43, v49, s[6:7]
	s_mov_b64 s[18:19], 0

; __device__ __forceinline__ float dpp_shr1(float old, float src) { return __builtin_bit_cast(float, __builtin_amdgcn_update_dpp(__builtin_bit_cast(int, old), __builtin_bit_cast(int, src), 0x111, 0xf, 0xf, false)); }
; __device__ __forceinline__ float dpp_shr2(float old, float src) { return __builtin_bit_cast(float, __builtin_amdgcn_update_dpp(__builtin_bit_cast(int, old), __builtin_bit_cast(int, src), 0x112, 0xf, 0xf, false)); }
;     __device__ __forceinline__ void operator()(const f32x4 (&acc)[2][2][4][2], const Unit& u, int wr, int wc, int fr, int fq) const {
;     ...
;                         const int t = fr & 7, bs = (r - MP) >> 3; f32x4 s0 = (f32x4){0.f, 0.f, 0.f, 0.f}, s1 = s0;
;                         if (t < 2) { s0 = *(const f32x4*)(st_ffn + ((size_t)bs * 2 + 0) * DFF + j0 + 4 * n); s1 = *(const f32x4*)(st_ffn + ((size_t)bs * 2 + 1) * DFF + j0 + 4 * n); }
; #pragma unroll
;                         for (int e = 0; e < 4; ++e) { const float a1 = dpp_shr1(0.f, g[e]), a2 = dpp_shr2(0.f, g[e]); p1[e] = (t >= 1) ? a1 : s1[e]; p2[e] = (t >= 2) ? a2 : (t == 1 ? s1[e] : s0[e]); }
;                         if (t >= 6) *(f32x4*)(out + O_SFFN + ((size_t)bs * 2 + (t - 6)) * DFF + j0 + 4 * n) = g;
.LBB0_879:
	s_or_b64 exec, exec, s[18:19]
	v_mov_b32_e32 v43, v179
	v_mov_b32_e32 v44, v179
	v_mov_b32_e32 v45, v179
	v_mov_b32_e32 v46, v179
	v_mov_b32_e32 v47, v179
	v_mov_b32_e32 v48, v179
	v_mov_b32_e32 v49, v179
	v_mov_b32_e32 v41, v179
	v_mov_b32_dpp v43, v26 row_shr:1 row_mask:0xf bank_mask:0xf
	v_mov_b32_dpp v44, v26 row_shr:2 row_mask:0xf bank_mask:0xf
	v_mov_b32_dpp v45, v27 row_shr:1 row_mask:0xf bank_mask:0xf
	v_mov_b32_dpp v46, v27 row_shr:2 row_mask:0xf bank_mask:0xf
	v_mov_b32_dpp v47, v28 row_shr:1 row_mask:0xf bank_mask:0xf
	v_mov_b32_dpp v48, v28 row_shr:2 row_mask:0xf bank_mask:0xf
	v_mov_b32_dpp v49, v29 row_shr:1 row_mask:0xf bank_mask:0xf
	v_mov_b32_dpp v41, v29 row_shr:2 row_mask:0xf bank_mask:0xf
	s_waitcnt vmcnt(0)
	s_and_saveexec_b64 s[18:19], s[12:13]
	s_cbranch_execz .LBB0_881
	v_ashrrev_i32_e32 v31, 31, v30
	v_lshl_add_u64 v[30:31], v[30:31], 1, v[178:179]
	v_mov_b64_e32 v[50:51], s[34:35]
	v_mad_u64_u32 v[50:51], s[20:21], v30, s26, v[50:51]
	v_mad_i32_i24 v51, v31, s26, v51
	v_lshl_add_u64 v[30:31], v[184:185], 2, v[50:51]
	v_add_co_u32_e32 v30, vcc, 0x15c86000, v30
	s_nop 1
	v_addc_co_u32_e32 v31, vcc, 0, v31, vcc
	global_store_dwordx4 v[30:31], v[26:29], off offset:16
.LBB0_881:
	s_or_b64 exec, exec, s[18:19]
	v_cndmask_b32_e64 v31, v32, v36, s[8:9]
	v_cndmask_b32_e64 v32, v33, v37, s[8:9]
	v_cndmask_b32_e64 v33, v34, v38, s[8:9]
	v_cndmask_b32_e64 v35, v35, v39, s[8:9]
	v_cndmask_b32_e64 v30, v43, v36, s[10:11]
	v_cndmask_b32_e64 v36, v31, v44, s[6:7]
	v_cndmask_b32_e64 v31, v45, v37, s[10:11]
	v_cndmask_b32_e64 v37, v32, v46, s[6:7]
	v_cndmask_b32_e64 v32, v47, v38, s[10:11]
	v_cndmask_b32_e64 v34, v33, v48, s[6:7]
	v_cndmask_b32_e64 v33, v49, v39, s[10:11]
	v_cndmask_b32_e64 v35, v35, v41, s[6:7]
	s_mov_b64 s[18:19], 0

; __device__ __forceinline__ float dpp_shr1(float old, float src) { return __builtin_bit_cast(float, __builtin_amdgcn_update_dpp(__builtin_bit_cast(int, old), __builtin_bit_cast(int, src), 0x111, 0xf, 0xf, false)); }
; __device__ __forceinline__ float dpp_shr2(float old, float src) { return __builtin_bit_cast(float, __builtin_amdgcn_update_dpp(__builtin_bit_cast(int, old), __builtin_bit_cast(int, src), 0x112, 0xf, 0xf, false)); }
;     __device__ __forceinline__ void operator()(const f32x4 (&acc)[2][2][4][2], const Unit& u, int wr, int wc, int fr, int fq) const {
;     ...
;                         const int t = fr & 7, bs = (r - MP) >> 3; f32x4 s0 = (f32x4){0.f, 0.f, 0.f, 0.f}, s1 = s0;
;                         if (t < 2) { s0 = *(const f32x4*)(st_ffn + ((size_t)bs * 2 + 0) * DFF + j0 + 4 * n); s1 = *(const f32x4*)(st_ffn + ((size_t)bs * 2 + 1) * DFF + j0 + 4 * n); }
; #pragma unroll
;                         for (int e = 0; e < 4; ++e) { const float a1 = dpp_shr1(0.f, g[e]), a2 = dpp_shr2(0.f, g[e]); p1[e] = (t >= 1) ? a1 : s1[e]; p2[e] = (t >= 2) ? a2 : (t == 1 ? s1[e] : s0[e]); }
;                         if (t >= 6) *(f32x4*)(out + O_SFFN + ((size_t)bs * 2 + (t - 6)) * DFF + j0 + 4 * n) = g;
.LBB0_887:
	s_or_b64 exec, exec, s[16:17]
	v_mov_b32_e32 v31, v179
	v_mov_b32_e32 v32, v179
	v_mov_b32_e32 v33, v179
	v_mov_b32_e32 v34, v179
	v_mov_b32_e32 v35, v179
	v_mov_b32_e32 v36, v179
	v_mov_b32_e32 v37, v179
	v_mov_b32_e32 v29, v179
	v_mov_b32_dpp v31, v14 row_shr:1 row_mask:0xf bank_mask:0xf
	v_mov_b32_dpp v32, v14 row_shr:2 row_mask:0xf bank_mask:0xf
	v_mov_b32_dpp v33, v15 row_shr:1 row_mask:0xf bank_mask:0xf
	v_mov_b32_dpp v34, v15 row_shr:2 row_mask:0xf bank_mask:0xf
	v_mov_b32_dpp v35, v16 row_shr:1 row_mask:0xf bank_mask:0xf
	v_mov_b32_dpp v36, v16 row_shr:2 row_mask:0xf bank_mask:0xf
	v_mov_b32_dpp v37, v17 row_shr:1 row_mask:0xf bank_mask:0xf
	v_mov_b32_dpp v29, v17 row_shr:2 row_mask:0xf bank_mask:0xf
	s_waitcnt vmcnt(0)
	s_and_saveexec_b64 s[14:15], s[12:13]
	s_cbranch_execz .LBB0_889
	v_ashrrev_i32_e32 v19, 31, v18
	v_lshl_add_u64 v[18:19], v[18:19], 1, v[178:179]
	v_mov_b64_e32 v[38:39], s[34:35]
	v_mad_u64_u32 v[38:39], s[12:13], v18, s26, v[38:39]
	v_mad_i32_i24 v39, v19, s26, v39
	v_lshl_add_u64 v[18:19], v[184:185], 2, v[38:39]
	v_add_co_u32_e32 v18, vcc, 0x15c86000, v18
	s_nop 1
	v_addc_co_u32_e32 v19, vcc, 0, v19, vcc
	global_store_dwordx4 v[18:19], v[14:17], off offset:16
.LBB0_889:
	s_or_b64 exec, exec, s[14:15]
	v_cndmask_b32_e64 v19, v20, v24, s[8:9]
	v_cndmask_b32_e64 v20, v21, v25, s[8:9]
	v_cndmask_b32_e64 v21, v22, v26, s[8:9]
	v_cndmask_b32_e64 v23, v23, v27, s[8:9]
	v_cndmask_b32_e64 v18, v31, v24, s[10:11]
	v_cndmask_b32_e64 v24, v19, v32, s[6:7]
	v_cndmask_b32_e64 v19, v33, v25, s[10:11]
	v_cndmask_b32_e64 v25, v20, v34, s[6:7]
	v_cndmask_b32_e64 v20, v35, v26, s[10:11]
	v_cndmask_b32_e64 v22, v21, v36, s[6:7]
	v_cndmask_b32_e64 v21, v37, v27, s[10:11]
	v_cndmask_b32_e64 v23, v23, v29, s[6:7]
	s_mov_b64 s[16:17], 0
